# top-k bisection loop control moved to SALU (T, bit, candidate in SGPRs; wave-uniform exit test without the VALU->vcc->branch chain), the two sorted blocks' select trees interleaved
# speedup vs baseline: 1.0070x; 1.0070x over previous
.LBB0_890:
	s_or_b64 exec, exec, s[0:1]
	v_readlane_b32 s0, v254, 51
	v_readlane_b32 s4, v254, 29
	s_lshl_b32 s0, s0, 8
	v_readlane_b32 s18, v254, 43
	v_and_b32_e32 v16, 63, v43
	v_readlane_b32 s1, v254, 52
	v_readlane_b32 s19, v254, 44
	s_add_u32 s0, s18, s0
	v_ashrrev_i32_e32 v43, 31, v42
	s_addc_u32 s1, s19, 0
	v_mul_u32_u24_e32 v2, 0x4100, v47
	v_lshlrev_b64 v[0:1], 8, v[42:43]
	v_lshlrev_b32_e32 v3, 2, v16
	v_lshl_add_u64 v[0:1], s[0:1], 0, v[0:1]
	s_cmpk_lt_u32 s71, 0xc00
	s_waitcnt vmcnt(3)
	v_add3_u32 v28, v46, v2, v3
	v_readlane_b32 s5, v254, 30
	v_readlane_b32 s6, v254, 31
	v_readlane_b32 s7, v254, 32
	v_readlane_b32 s8, v254, 33
	v_readlane_b32 s9, v254, 34
	v_readlane_b32 s10, v254, 35
	v_readlane_b32 s11, v254, 36
	v_readlane_b32 s12, v254, 37
	v_readlane_b32 s13, v254, 38
	v_readlane_b32 s14, v254, 39
	v_readlane_b32 s15, v254, 40
	v_readlane_b32 s16, v254, 41
	v_readlane_b32 s17, v254, 42
	s_waitcnt lgkmcnt(0)
	s_barrier
	s_cbranch_scc0 .LBB0_1038
	s_cmpk_lt_u32 s71, 0x800
	s_cbranch_scc0 .LBB0_1043
	s_cmpk_lt_u32 s71, 0x400
	s_cbranch_scc0 .LBB0_1044
	ds_read2st64_b32 v[26:27], v28 offset1:1
	ds_read2st64_b32 v[24:25], v28 offset0:2 offset1:3
	ds_read2st64_b32 v[22:23], v28 offset0:4 offset1:5
	ds_read2st64_b32 v[20:21], v28 offset0:6 offset1:7
	ds_read2st64_b32 v[18:19], v28 offset0:8 offset1:9
	ds_read2st64_b32 v[14:15], v28 offset0:10 offset1:11
	ds_read2st64_b32 v[12:13], v28 offset0:12 offset1:13
	ds_read2st64_b32 v[10:11], v28 offset0:14 offset1:15
	ds_read2st64_b32 v[8:9], v28 offset0:16 offset1:17
	ds_read2st64_b32 v[6:7], v28 offset0:18 offset1:19
	ds_read2st64_b32 v[4:5], v28 offset0:20 offset1:21
	ds_read2st64_b32 v[2:3], v28 offset0:22 offset1:23
	v_or_b32_e32 v29, 0x600, v16
	v_cmp_gt_u32_e32 vcc, s72, v29
	s_waitcnt vmcnt(1)
	v_mov_b32_e32 v36, 0
	v_mov_b32_e32 v37, 0
	s_and_saveexec_b64 s[0:1], vcc
	ds_read_b32 v37, v28 offset:6144
	s_or_b64 exec, exec, s[0:1]
	v_or_b32_e32 v29, 0x640, v16
	v_cmp_gt_u32_e32 vcc, s72, v29
	s_and_saveexec_b64 s[0:1], vcc
	ds_read_b32 v36, v28 offset:6400
	s_or_b64 exec, exec, s[0:1]
	v_or_b32_e32 v29, 0x680, v16
	v_cmp_gt_u32_e32 vcc, s72, v29
	v_mov_b32_e32 v34, 0
	v_mov_b32_e32 v35, 0
	s_and_saveexec_b64 s[0:1], vcc
	ds_read_b32 v35, v28 offset:6656
	s_or_b64 exec, exec, s[0:1]
	v_or_b32_e32 v29, 0x6c0, v16
	v_cmp_gt_u32_e32 vcc, s72, v29
	s_and_saveexec_b64 s[0:1], vcc
	ds_read_b32 v34, v28 offset:6912
	s_or_b64 exec, exec, s[0:1]
	v_or_b32_e32 v29, 0x700, v16
	v_cmp_gt_u32_e32 vcc, s72, v29
	v_mov_b32_e32 v32, 0
	v_mov_b32_e32 v33, 0
	s_and_saveexec_b64 s[0:1], vcc
	ds_read_b32 v33, v28 offset:7168
	s_or_b64 exec, exec, s[0:1]
	v_or_b32_e32 v29, 0x740, v16
	v_cmp_gt_u32_e32 vcc, s72, v29
	s_and_saveexec_b64 s[0:1], vcc
	ds_read_b32 v32, v28 offset:7424
	s_or_b64 exec, exec, s[0:1]
	v_or_b32_e32 v29, 0x780, v16
	v_cmp_gt_u32_e32 vcc, s72, v29
	v_mov_b32_e32 v29, 0
	v_mov_b32_e32 v31, 0
	s_and_saveexec_b64 s[0:1], vcc
	ds_read_b32 v31, v28 offset:7680
	s_or_b64 exec, exec, s[0:1]
	v_or_b32_e32 v30, 0x7c0, v16
	v_cmp_gt_u32_e32 vcc, s72, v30
	s_and_saveexec_b64 s[0:1], vcc
	ds_read_b32 v29, v28 offset:7936
	s_or_b64 exec, exec, s[0:1]
	s_waitcnt vmcnt(0)
	v_mov_b32_e32 v38, 31
	v_mov_b32_e32 v30, 0
	s_waitcnt lgkmcnt(0)
	s_waitcnt vmcnt(0)
	v_max_u32_e32 v142, v26, v18
	v_min_u32_e32 v143, v26, v18
	v_max_u32_e32 v144, v27, v19
	v_min_u32_e32 v145, v27, v19
	v_max_u32_e32 v146, v24, v14
	v_min_u32_e32 v147, v24, v14
	v_max_u32_e32 v148, v25, v15
	v_min_u32_e32 v149, v25, v15
	v_max_u32_e32 v150, v22, v12
	v_min_u32_e32 v151, v22, v12
	v_max_u32_e32 v152, v23, v13
	v_min_u32_e32 v153, v23, v13
	v_max_u32_e32 v154, v20, v10
	v_min_u32_e32 v155, v20, v10
	v_max_u32_e32 v156, v21, v11
	v_min_u32_e32 v157, v21, v11
	v_max_u32_e32 v158, v142, v150
	v_min_u32_e32 v159, v142, v150
	v_max_u32_e32 v150, v144, v152
	v_min_u32_e32 v142, v144, v152
	v_max_u32_e32 v152, v146, v154
	v_min_u32_e32 v144, v146, v154
	v_max_u32_e32 v154, v148, v156
	v_min_u32_e32 v146, v148, v156
	v_max_u32_e32 v156, v143, v151
	v_min_u32_e32 v148, v143, v151
	v_max_u32_e32 v151, v145, v153
	v_min_u32_e32 v143, v145, v153
	v_max_u32_e32 v153, v147, v155
	v_min_u32_e32 v145, v147, v155
	v_max_u32_e32 v155, v149, v157
	v_min_u32_e32 v147, v149, v157
	v_max_u32_e32 v157, v159, v156
	v_min_u32_e32 v149, v159, v156
	v_max_u32_e32 v156, v142, v151
	v_min_u32_e32 v159, v142, v151
	v_max_u32_e32 v151, v144, v153
	v_min_u32_e32 v142, v144, v153
	v_max_u32_e32 v153, v146, v155
	v_min_u32_e32 v144, v146, v155
	v_max_u32_e32 v155, v158, v152
	v_min_u32_e32 v146, v158, v152
	v_max_u32_e32 v152, v150, v154
	v_min_u32_e32 v158, v150, v154
	v_max_u32_e32 v154, v157, v151
	v_min_u32_e32 v150, v157, v151
	v_max_u32_e32 v151, v156, v153
	v_min_u32_e32 v157, v156, v153
	v_max_u32_e32 v153, v149, v142
	v_min_u32_e32 v156, v149, v142
	v_max_u32_e32 v142, v159, v144
	v_min_u32_e32 v149, v159, v144
	v_max_u32_e32 v144, v148, v145
	v_min_u32_e32 v159, v148, v145
	v_max_u32_e32 v145, v143, v147
	v_min_u32_e32 v148, v143, v147
	v_max_u32_e32 v147, v146, v153
	v_min_u32_e32 v143, v146, v153
	v_max_u32_e32 v153, v158, v142
	v_min_u32_e32 v146, v158, v142
	v_max_u32_e32 v142, v150, v144
	v_min_u32_e32 v158, v150, v144
	v_max_u32_e32 v144, v157, v145
	v_min_u32_e32 v150, v157, v145
	v_max_u32_e32 v145, v147, v154
	v_min_u32_e32 v157, v147, v154
	v_max_u32_e32 v154, v153, v151
	v_min_u32_e32 v147, v153, v151
	v_max_u32_e32 v151, v142, v143
	v_min_u32_e32 v153, v142, v143
	v_max_u32_e32 v143, v144, v146
	v_min_u32_e32 v142, v144, v146
	v_max_u32_e32 v146, v156, v158
	v_min_u32_e32 v144, v156, v158
	v_max_u32_e32 v158, v149, v150
	v_min_u32_e32 v156, v149, v150
	v_max_u32_e32 v150, v155, v152
	v_min_u32_e32 v149, v155, v152
	v_max_u32_e32 v152, v145, v154
	v_min_u32_e32 v155, v145, v154
	v_max_u32_e32 v154, v157, v147
	v_min_u32_e32 v145, v157, v147
	v_max_u32_e32 v147, v151, v143
	v_min_u32_e32 v157, v151, v143
	v_max_u32_e32 v143, v153, v142
	v_min_u32_e32 v151, v153, v142
	v_max_u32_e32 v142, v146, v158
	v_min_u32_e32 v153, v146, v158
	v_max_u32_e32 v158, v144, v156
	v_min_u32_e32 v146, v144, v156
	v_max_u32_e32 v156, v159, v148
	v_min_u32_e32 v144, v159, v148
	v_max_u32_e32 v148, v149, v143
	v_min_u32_e32 v159, v149, v143
	v_max_u32_e32 v143, v155, v142
	v_min_u32_e32 v149, v155, v142
	v_max_u32_e32 v142, v145, v158
	v_min_u32_e32 v155, v145, v158
	v_max_u32_e32 v158, v157, v156
	v_min_u32_e32 v145, v157, v156
	v_max_u32_e32 v156, v148, v154
	v_min_u32_e32 v157, v148, v154
	v_max_u32_e32 v154, v143, v147
	v_min_u32_e32 v148, v143, v147
	v_max_u32_e32 v147, v142, v159
	v_min_u32_e32 v143, v142, v159
	v_max_u32_e32 v159, v158, v149
	v_min_u32_e32 v142, v158, v149
	v_max_u32_e32 v149, v151, v155
	v_min_u32_e32 v158, v151, v155
	v_max_u32_e32 v155, v153, v145
	v_min_u32_e32 v151, v153, v145
	v_max_u32_e32 v145, v156, v152
	v_min_u32_e32 v153, v156, v152
	v_max_u32_e32 v152, v154, v157
	v_min_u32_e32 v156, v154, v157
	v_max_u32_e32 v157, v147, v148
	v_min_u32_e32 v154, v147, v148
	v_max_u32_e32 v148, v159, v143
	v_min_u32_e32 v147, v159, v143
	v_max_u32_e32 v143, v149, v142
	v_min_u32_e32 v159, v149, v142
	v_max_u32_e32 v142, v155, v158
	v_min_u32_e32 v149, v155, v158
	v_max_u32_e32 v158, v146, v151
	v_min_u32_e32 v155, v146, v151
	v_max_u32_e32 v151, v8, v37
	v_min_u32_e32 v146, v8, v37
	v_max_u32_e32 v160, v9, v36
	v_min_u32_e32 v161, v9, v36
	v_max_u32_e32 v162, v6, v35
	v_min_u32_e32 v163, v6, v35
	v_max_u32_e32 v164, v7, v34
	v_min_u32_e32 v165, v7, v34
	v_max_u32_e32 v166, v4, v33
	v_min_u32_e32 v167, v4, v33
	v_max_u32_e32 v168, v5, v32
	v_min_u32_e32 v169, v5, v32
	v_max_u32_e32 v170, v2, v31
	v_min_u32_e32 v171, v2, v31
	v_max_u32_e32 v172, v3, v29
	v_min_u32_e32 v173, v3, v29
	v_max_u32_e32 v174, v151, v166
	v_min_u32_e32 v175, v151, v166
	v_max_u32_e32 v166, v160, v168
	v_min_u32_e32 v151, v160, v168
	v_max_u32_e32 v168, v162, v170
	v_min_u32_e32 v160, v162, v170
	v_max_u32_e32 v170, v164, v172
	v_min_u32_e32 v162, v164, v172
	v_max_u32_e32 v172, v146, v167
	v_min_u32_e32 v164, v146, v167
	v_max_u32_e32 v167, v161, v169
	v_min_u32_e32 v146, v161, v169
	v_max_u32_e32 v169, v163, v171
	v_min_u32_e32 v161, v163, v171
	v_max_u32_e32 v171, v165, v173
	v_min_u32_e32 v163, v165, v173
	v_max_u32_e32 v173, v175, v172
	v_min_u32_e32 v165, v175, v172
	v_max_u32_e32 v172, v151, v167
	v_min_u32_e32 v175, v151, v167
	v_max_u32_e32 v167, v160, v169
	v_min_u32_e32 v151, v160, v169
	v_max_u32_e32 v169, v162, v171
	v_min_u32_e32 v160, v162, v171
	v_max_u32_e32 v171, v174, v168
	v_min_u32_e32 v162, v174, v168
	v_max_u32_e32 v168, v166, v170
	v_min_u32_e32 v174, v166, v170
	v_max_u32_e32 v170, v173, v167
	v_min_u32_e32 v166, v173, v167
	v_max_u32_e32 v167, v172, v169
	v_min_u32_e32 v173, v172, v169
	v_max_u32_e32 v169, v165, v151
	v_min_u32_e32 v172, v165, v151
	v_max_u32_e32 v151, v175, v160
	v_min_u32_e32 v165, v175, v160
	v_max_u32_e32 v160, v164, v161
	v_min_u32_e32 v175, v164, v161
	v_max_u32_e32 v161, v146, v163
	v_min_u32_e32 v164, v146, v163
	v_max_u32_e32 v163, v162, v169
	v_min_u32_e32 v146, v162, v169
	v_max_u32_e32 v169, v174, v151
	v_min_u32_e32 v162, v174, v151
	v_max_u32_e32 v151, v166, v160
	v_min_u32_e32 v174, v166, v160
	v_max_u32_e32 v160, v173, v161
	v_min_u32_e32 v166, v173, v161
	v_max_u32_e32 v161, v163, v170
	v_min_u32_e32 v173, v163, v170
	v_max_u32_e32 v170, v169, v167
	v_min_u32_e32 v163, v169, v167
	v_max_u32_e32 v167, v151, v146
	v_min_u32_e32 v169, v151, v146
	v_max_u32_e32 v146, v160, v162
	v_min_u32_e32 v151, v160, v162
	v_max_u32_e32 v162, v172, v174
	v_min_u32_e32 v160, v172, v174
	v_max_u32_e32 v174, v165, v166
	v_min_u32_e32 v172, v165, v166
	v_max_u32_e32 v166, v171, v168
	v_min_u32_e32 v165, v171, v168
	v_max_u32_e32 v168, v161, v170
	v_min_u32_e32 v171, v161, v170
	v_max_u32_e32 v170, v173, v163
	v_min_u32_e32 v161, v173, v163
	v_max_u32_e32 v163, v167, v146
	v_min_u32_e32 v173, v167, v146
	v_max_u32_e32 v146, v169, v151
	v_min_u32_e32 v167, v169, v151
	v_max_u32_e32 v151, v162, v174
	v_min_u32_e32 v169, v162, v174
	v_max_u32_e32 v174, v160, v172
	v_min_u32_e32 v162, v160, v172
	v_max_u32_e32 v172, v175, v164
	v_min_u32_e32 v160, v175, v164
	v_max_u32_e32 v164, v165, v146
	v_min_u32_e32 v175, v165, v146
	v_max_u32_e32 v146, v171, v151
	v_min_u32_e32 v165, v171, v151
	v_max_u32_e32 v151, v161, v174
	v_min_u32_e32 v171, v161, v174
	v_max_u32_e32 v174, v173, v172
	v_min_u32_e32 v161, v173, v172
	v_max_u32_e32 v172, v164, v170
	v_min_u32_e32 v173, v164, v170
	v_max_u32_e32 v170, v146, v163
	v_min_u32_e32 v164, v146, v163
	v_max_u32_e32 v163, v151, v175
	v_min_u32_e32 v146, v151, v175
	v_max_u32_e32 v175, v174, v165
	v_min_u32_e32 v151, v174, v165
	v_max_u32_e32 v165, v167, v171
	v_min_u32_e32 v174, v167, v171
	v_max_u32_e32 v171, v169, v161
	v_min_u32_e32 v167, v169, v161
	v_max_u32_e32 v161, v172, v168
	v_min_u32_e32 v169, v172, v168
	v_max_u32_e32 v168, v170, v173
	v_min_u32_e32 v172, v170, v173
	v_max_u32_e32 v173, v163, v164
	v_min_u32_e32 v170, v163, v164
	v_max_u32_e32 v164, v175, v146
	v_min_u32_e32 v163, v175, v146
	v_max_u32_e32 v146, v165, v151
	v_min_u32_e32 v175, v165, v151
	v_max_u32_e32 v151, v171, v174
	v_min_u32_e32 v165, v171, v174
	v_max_u32_e32 v174, v162, v167
	v_min_u32_e32 v171, v162, v167
	s_mov_b32 s12, 0
	s_mov_b32 s13, 31
.LBB0_910:
	s_lshl_b32 s14, 1, s13
	s_or_b32 s14, s14, s12
	v_cmp_ge_u32_e64 s[4:5], v148, s14
	v_cmp_ge_u32_e64 s[18:19], v164, s14
	v_cmp_ge_u32_e64 s[16:17], v144, s14
	v_cmp_ge_u32_e64 s[26:27], v160, s14
	v_cndmask_b32_e64 v134, v152, v142, s[4:5]
	v_cndmask_b32_e64 v138, v168, v151, s[18:19]
	v_cmp_ge_u32_e64 s[6:7], v134, s14
	v_cmp_ge_u32_e64 s[20:21], v138, s14
	s_nop 0
	v_cndmask_b32_e64 v134, v145, v157, s[6:7]
	v_cndmask_b32_e64 v138, v161, v173, s[20:21]
	v_cndmask_b32_e64 v135, v143, v158, s[6:7]
	v_cndmask_b32_e64 v139, v146, v174, s[20:21]
	v_cndmask_b32_e64 v134, v134, v135, s[4:5]
	v_cndmask_b32_e64 v138, v138, v139, s[18:19]
	v_cmp_ge_u32_e64 s[8:9], v134, s14
	v_cmp_ge_u32_e64 s[22:23], v138, s14
	s_nop 0
	v_cndmask_b32_e64 v134, v150, v153, s[8:9]
	v_cndmask_b32_e64 v138, v166, v169, s[22:23]
	v_cndmask_b32_e64 v135, v156, v154, s[8:9]
	v_cndmask_b32_e64 v139, v172, v170, s[22:23]
	v_cndmask_b32_e64 v136, v147, v159, s[8:9]
	v_cndmask_b32_e64 v140, v163, v175, s[22:23]
	v_cndmask_b32_e64 v137, v149, v155, s[8:9]
	v_cndmask_b32_e64 v141, v165, v171, s[22:23]
	v_cndmask_b32_e64 v134, v134, v135, s[6:7]
	v_cndmask_b32_e64 v138, v138, v139, s[20:21]
	v_cndmask_b32_e64 v136, v136, v137, s[6:7]
	v_cndmask_b32_e64 v140, v140, v141, s[20:21]
	v_cndmask_b32_e64 v134, v134, v136, s[4:5]
	v_cndmask_b32_e64 v138, v138, v140, s[18:19]
	v_cmp_ge_u32_e64 s[10:11], v134, s14
	v_cmp_ge_u32_e64 s[24:25], v138, s14
	s_bcnt1_i32_b64 s1, s[4:5]
	s_mov_b32 s0, s1
	s_bcnt1_i32_b64 s1, s[6:7]
	s_lshl1_add_u32 s0, s0, s1
	s_bcnt1_i32_b64 s1, s[8:9]
	s_lshl1_add_u32 s0, s0, s1
	s_bcnt1_i32_b64 s1, s[10:11]
	s_lshl1_add_u32 s0, s0, s1
	s_bcnt1_i32_b64 s1, s[16:17]
	s_add_i32 s0, s0, s1
	s_mov_b32 s2, s0
	s_bcnt1_i32_b64 s1, s[18:19]
	s_mov_b32 s0, s1
	s_bcnt1_i32_b64 s1, s[20:21]
	s_lshl1_add_u32 s0, s0, s1
	s_bcnt1_i32_b64 s1, s[22:23]
	s_lshl1_add_u32 s0, s0, s1
	s_bcnt1_i32_b64 s1, s[24:25]
	s_lshl1_add_u32 s0, s0, s1
	s_bcnt1_i32_b64 s1, s[26:27]
	s_add_i32 s0, s0, s1
	s_add_i32 s2, s2, s0
	s_cmpk_ge_u32 s2, 0x100
	s_cselect_b32 s12, s14, s12
	s_cmpk_eq_u32 s2, 0x100
	s_cbranch_scc1 .Lbt_exit_32
	s_sub_u32 s13, s13, 1
	s_cbranch_scc0 .LBB0_910
.Lbt_exit_32:
	v_mov_b32_e32 v30, s12
	s_cmpk_eq_i32 s2, 0x100
	s_cbranch_scc1 .Lselfast_32
	v_cmp_gt_u32_e32 vcc, v26, v30
	s_bcnt1_i32_b64 s8, vcc
	v_cmp_gt_u32_e32 vcc, v27, v30
	s_bcnt1_i32_b64 s9, vcc
	v_cmp_gt_u32_e32 vcc, v24, v30
	s_bcnt1_i32_b64 s10, vcc
	v_cmp_gt_u32_e32 vcc, v25, v30
	s_add_i32 s8, s8, s9
	s_bcnt1_i32_b64 s11, vcc
	v_cmp_gt_u32_e32 vcc, v22, v30
	s_add_i32 s8, s8, s10
	s_bcnt1_i32_b64 s64, vcc
	v_cmp_gt_u32_e32 vcc, v23, v30
	s_add_i32 s8, s8, s11
	s_bcnt1_i32_b64 s65, vcc
	v_cmp_gt_u32_e32 vcc, v20, v30
	s_add_i32 s8, s8, s64
	s_bcnt1_i32_b64 s66, vcc
	v_cmp_gt_u32_e32 vcc, v21, v30
	s_add_i32 s8, s8, s65
	s_bcnt1_i32_b64 s67, vcc
	v_cmp_gt_u32_e32 vcc, v18, v30
	s_add_i32 s64, s8, s66
	s_bcnt1_i32_b64 s68, vcc
	v_cmp_gt_u32_e32 vcc, v19, v30
	s_add_i32 s64, s64, s67
	s_bcnt1_i32_b64 s69, vcc
	v_cmp_gt_u32_e32 vcc, v14, v30
	s_add_i32 s64, s64, s68
	s_bcnt1_i32_b64 s73, vcc
	v_cmp_gt_u32_e32 vcc, v15, v30
	s_add_i32 s64, s64, s69
	s_bcnt1_i32_b64 s74, vcc
	v_cmp_gt_u32_e32 vcc, v12, v30
	s_add_i32 s64, s64, s73
	s_bcnt1_i32_b64 s75, vcc
	v_cmp_gt_u32_e32 vcc, v13, v30
	s_add_i32 s64, s64, s74
	s_bcnt1_i32_b64 s76, vcc
	v_cmp_gt_u32_e32 vcc, v10, v30
	s_add_i32 s64, s64, s75
	s_bcnt1_i32_b64 s77, vcc
	v_cmp_gt_u32_e32 vcc, v11, v30
	s_add_i32 s64, s64, s76
	s_bcnt1_i32_b64 s78, vcc
	v_cmp_gt_u32_e32 vcc, v8, v30
	s_add_i32 s64, s64, s77
	s_bcnt1_i32_b64 s79, vcc
	v_cmp_gt_u32_e32 vcc, v9, v30
	s_add_i32 s64, s64, s78
	s_bcnt1_i32_b64 s80, vcc
	v_cmp_gt_u32_e32 vcc, v6, v30
	s_add_i32 s64, s64, s79
	s_bcnt1_i32_b64 s81, vcc
	v_cmp_gt_u32_e32 vcc, v7, v30
	s_add_i32 s64, s64, s80
	s_bcnt1_i32_b64 s82, vcc
	v_cmp_gt_u32_e32 vcc, v4, v30
	s_add_i32 s64, s64, s81
	s_bcnt1_i32_b64 s83, vcc
	v_cmp_gt_u32_e32 vcc, v5, v30
	s_add_i32 s64, s64, s82
	s_bcnt1_i32_b64 s84, vcc
	v_cmp_gt_u32_e32 vcc, v2, v30
	s_add_i32 s64, s64, s83
	s_bcnt1_i32_b64 s85, vcc
	v_cmp_gt_u32_e32 vcc, v3, v30
	s_add_i32 s64, s64, s84
	s_bcnt1_i32_b64 s86, vcc
	v_cmp_gt_u32_e32 vcc, v37, v30
	s_add_i32 s64, s64, s85
	s_bcnt1_i32_b64 s87, vcc
	v_cmp_gt_u32_e32 vcc, v36, v30
	s_add_i32 s64, s64, s86
	s_bcnt1_i32_b64 s88, vcc
	v_cmp_gt_u32_e32 vcc, v35, v30
	s_add_i32 s64, s64, s87
	s_bcnt1_i32_b64 s89, vcc
	v_cmp_gt_u32_e32 vcc, v34, v30
	s_add_i32 s64, s64, s88
	s_bcnt1_i32_b64 s90, vcc
	v_cmp_gt_u32_e32 vcc, v33, v30
	s_add_i32 s64, s64, s89
	s_bcnt1_i32_b64 s91, vcc
	v_cmp_gt_u32_e32 vcc, v32, v30
	s_add_i32 s64, s64, s90
	s_bcnt1_i32_b64 s92, vcc
	v_cmp_gt_u32_e32 vcc, v31, v30
	s_add_i32 s64, s64, s91
	s_bcnt1_i32_b64 s93, vcc
	v_cmp_gt_u32_e32 vcc, v29, v30
	s_add_i32 s64, s64, s92
	s_bcnt1_i32_b64 s94, vcc
	s_add_i32 s64, s64, s93
	s_add_i32 s64, s64, s94
	v_cmp_le_u32_e64 s[62:63], v26, v30
	v_cmp_le_u32_e64 s[60:61], v27, v30
	v_cmp_le_u32_e64 s[58:59], v24, v30
	v_cmp_le_u32_e64 s[56:57], v25, v30
	v_cmp_le_u32_e64 s[54:55], v22, v30
	v_cmp_le_u32_e64 s[52:53], v23, v30
	v_cmp_le_u32_e64 s[50:51], v20, v30
	v_cmp_le_u32_e64 s[48:49], v21, v30
	v_cmp_le_u32_e64 s[46:47], v18, v30
	v_cmp_le_u32_e64 s[44:45], v19, v30
	v_cmp_le_u32_e64 s[42:43], v14, v30
	v_cmp_le_u32_e64 s[40:41], v15, v30
	v_cmp_le_u32_e64 s[38:39], v12, v30
	v_cmp_le_u32_e64 s[36:37], v13, v30
	v_cmp_le_u32_e64 s[34:35], v10, v30
	v_cmp_le_u32_e64 s[30:31], v11, v30
	v_cmp_le_u32_e64 s[28:29], v8, v30
	v_cmp_le_u32_e64 s[26:27], v9, v30
	v_cmp_le_u32_e64 s[24:25], v6, v30
	v_cmp_le_u32_e64 s[22:23], v7, v30
	v_cmp_le_u32_e64 s[4:5], v4, v30
	v_cmp_le_u32_e64 s[0:1], v5, v30
	v_cmp_le_u32_e64 s[2:3], v2, v30
	v_cmp_le_u32_e64 s[6:7], v3, v30
	v_cmp_le_u32_e64 s[20:21], v37, v30
	v_cmp_le_u32_e64 s[18:19], v36, v30
	v_cmp_le_u32_e64 s[16:17], v35, v30
	v_cmp_le_u32_e64 s[14:15], v34, v30
	v_cmp_le_u32_e64 s[12:13], v33, v30
	v_cmp_le_u32_e64 s[10:11], v32, v30
	v_cmp_le_u32_e64 s[8:9], v31, v30
	v_cmp_le_u32_e32 vcc, v29, v30
	s_sub_i32 s73, 0x100, s64
	v_cmp_eq_u32_e64 s[64:65], v26, v30
	s_mov_b64 s[68:69], -1
	s_and_saveexec_b64 s[66:67], s[62:63]
	v_mbcnt_lo_u32_b32 v26, s64, 0
	v_mbcnt_hi_u32_b32 v26, s65, v26
	v_cmp_gt_i32_e64 s[62:63], s73, v26
	s_and_b64 s[62:63], s[64:65], s[62:63]
	s_orn2_b64 s[68:69], s[62:63], exec
	s_or_b64 exec, exec, s[66:67]
	v_cndmask_b32_e64 v26, 0, 1, s[68:69]
	v_cmp_eq_u32_e64 s[66:67], 0, v16
	v_cmp_ne_u32_e64 s[68:69], 0, v26
	s_and_saveexec_b64 s[62:63], s[66:67]
	s_cbranch_execz .LBB0_915
	v_mov_b64_e32 v[38:39], s[68:69]
	global_store_dwordx2 v[0:1], v[38:39], off

.LBB0_1044:
	s_mov_b64 s[66:67], 0
	s_mov_b64 s[2:3], 0xf8
	s_cbranch_execz .LBB0_1158
	ds_read2st64_b32 v[18:19], v28 offset1:1
	ds_read2st64_b32 v[14:15], v28 offset0:2 offset1:3
	ds_read2st64_b32 v[12:13], v28 offset0:4 offset1:5
	ds_read2st64_b32 v[10:11], v28 offset0:6 offset1:7
	ds_read2st64_b32 v[8:9], v28 offset0:8 offset1:9
	ds_read2st64_b32 v[6:7], v28 offset0:10 offset1:11
	ds_read2st64_b32 v[4:5], v28 offset0:12 offset1:13
	ds_read2st64_b32 v[2:3], v28 offset0:14 offset1:15
	v_or_b32_e32 v20, 0x400, v16
	v_cmp_gt_u32_e32 vcc, s72, v20
	v_mov_b32_e32 v27, 0
	v_mov_b32_e32 v29, 0
	s_and_saveexec_b64 s[0:1], vcc
	ds_read_b32 v29, v28 offset:4096
	s_or_b64 exec, exec, s[0:1]
	v_or_b32_e32 v20, 0x440, v16
	v_cmp_gt_u32_e32 vcc, s72, v20
	s_and_saveexec_b64 s[0:1], vcc
	ds_read_b32 v27, v28 offset:4352
	s_or_b64 exec, exec, s[0:1]
	v_or_b32_e32 v20, 0x480, v16
	v_cmp_gt_u32_e32 vcc, s72, v20
	v_mov_b32_e32 v25, 0
	v_mov_b32_e32 v26, 0
	s_and_saveexec_b64 s[0:1], vcc
	ds_read_b32 v26, v28 offset:4608
	s_or_b64 exec, exec, s[0:1]
	v_or_b32_e32 v20, 0x4c0, v16
	v_cmp_gt_u32_e32 vcc, s72, v20
	s_and_saveexec_b64 s[0:1], vcc
	ds_read_b32 v25, v28 offset:4864
	s_or_b64 exec, exec, s[0:1]
	v_or_b32_e32 v20, 0x500, v16
	v_cmp_gt_u32_e32 vcc, s72, v20
	v_mov_b32_e32 v23, 0
	v_mov_b32_e32 v24, 0
	s_and_saveexec_b64 s[0:1], vcc
	ds_read_b32 v24, v28 offset:5120
	s_or_b64 exec, exec, s[0:1]
	v_or_b32_e32 v20, 0x540, v16
	v_cmp_gt_u32_e32 vcc, s72, v20
	s_and_saveexec_b64 s[0:1], vcc
	ds_read_b32 v23, v28 offset:5376
	s_or_b64 exec, exec, s[0:1]
	v_or_b32_e32 v20, 0x580, v16
	v_cmp_gt_u32_e32 vcc, s72, v20
	v_mov_b32_e32 v20, 0
	v_mov_b32_e32 v22, 0
	s_and_saveexec_b64 s[0:1], vcc
	ds_read_b32 v22, v28 offset:5632
	s_or_b64 exec, exec, s[0:1]
	v_or_b32_e32 v21, 0x5c0, v16
	v_cmp_gt_u32_e32 vcc, s72, v21
	s_and_saveexec_b64 s[0:1], vcc
	ds_read_b32 v20, v28 offset:5888
	s_or_b64 exec, exec, s[0:1]
	s_waitcnt vmcnt(2)
	v_mov_b32_e32 v30, 31
	v_mov_b32_e32 v21, 0
	s_waitcnt lgkmcnt(0)
	s_waitcnt vmcnt(0)
	v_max_u32_e32 v142, v18, v8
	v_min_u32_e32 v143, v18, v8
	v_max_u32_e32 v144, v19, v9
	v_min_u32_e32 v145, v19, v9
	v_max_u32_e32 v146, v14, v6
	v_min_u32_e32 v147, v14, v6
	v_max_u32_e32 v148, v15, v7
	v_min_u32_e32 v149, v15, v7
	v_max_u32_e32 v150, v12, v4
	v_min_u32_e32 v151, v12, v4
	v_max_u32_e32 v152, v13, v5
	v_min_u32_e32 v153, v13, v5
	v_max_u32_e32 v154, v10, v2
	v_min_u32_e32 v155, v10, v2
	v_max_u32_e32 v156, v11, v3
	v_min_u32_e32 v157, v11, v3
	v_max_u32_e32 v158, v142, v150
	v_min_u32_e32 v159, v142, v150
	v_max_u32_e32 v150, v144, v152
	v_min_u32_e32 v142, v144, v152
	v_max_u32_e32 v152, v146, v154
	v_min_u32_e32 v144, v146, v154
	v_max_u32_e32 v154, v148, v156
	v_min_u32_e32 v146, v148, v156
	v_max_u32_e32 v156, v143, v151
	v_min_u32_e32 v148, v143, v151
	v_max_u32_e32 v151, v145, v153
	v_min_u32_e32 v143, v145, v153
	v_max_u32_e32 v153, v147, v155
	v_min_u32_e32 v145, v147, v155
	v_max_u32_e32 v155, v149, v157
	v_min_u32_e32 v147, v149, v157
	v_max_u32_e32 v157, v159, v156
	v_min_u32_e32 v149, v159, v156
	v_max_u32_e32 v156, v142, v151
	v_min_u32_e32 v159, v142, v151
	v_max_u32_e32 v151, v144, v153
	v_min_u32_e32 v142, v144, v153
	v_max_u32_e32 v153, v146, v155
	v_min_u32_e32 v144, v146, v155
	v_max_u32_e32 v155, v158, v152
	v_min_u32_e32 v146, v158, v152
	v_max_u32_e32 v152, v150, v154
	v_min_u32_e32 v158, v150, v154
	v_max_u32_e32 v154, v157, v151
	v_min_u32_e32 v150, v157, v151
	v_max_u32_e32 v151, v156, v153
	v_min_u32_e32 v157, v156, v153
	v_max_u32_e32 v153, v149, v142
	v_min_u32_e32 v156, v149, v142
	v_max_u32_e32 v142, v159, v144
	v_min_u32_e32 v149, v159, v144
	v_max_u32_e32 v144, v148, v145
	v_min_u32_e32 v159, v148, v145
	v_max_u32_e32 v145, v143, v147
	v_min_u32_e32 v148, v143, v147
	v_max_u32_e32 v147, v146, v153
	v_min_u32_e32 v143, v146, v153
	v_max_u32_e32 v153, v158, v142
	v_min_u32_e32 v146, v158, v142
	v_max_u32_e32 v142, v150, v144
	v_min_u32_e32 v158, v150, v144
	v_max_u32_e32 v144, v157, v145
	v_min_u32_e32 v150, v157, v145
	v_max_u32_e32 v145, v147, v154
	v_min_u32_e32 v157, v147, v154
	v_max_u32_e32 v154, v153, v151
	v_min_u32_e32 v147, v153, v151
	v_max_u32_e32 v151, v142, v143
	v_min_u32_e32 v153, v142, v143
	v_max_u32_e32 v143, v144, v146
	v_min_u32_e32 v142, v144, v146
	v_max_u32_e32 v146, v156, v158
	v_min_u32_e32 v144, v156, v158
	v_max_u32_e32 v158, v149, v150
	v_min_u32_e32 v156, v149, v150
	v_max_u32_e32 v150, v155, v152
	v_min_u32_e32 v149, v155, v152
	v_max_u32_e32 v152, v145, v154
	v_min_u32_e32 v155, v145, v154
	v_max_u32_e32 v154, v157, v147
	v_min_u32_e32 v145, v157, v147
	v_max_u32_e32 v147, v151, v143
	v_min_u32_e32 v157, v151, v143
	v_max_u32_e32 v143, v153, v142
	v_min_u32_e32 v151, v153, v142
	v_max_u32_e32 v142, v146, v158
	v_min_u32_e32 v153, v146, v158
	v_max_u32_e32 v158, v144, v156
	v_min_u32_e32 v146, v144, v156
	v_max_u32_e32 v156, v159, v148
	v_min_u32_e32 v144, v159, v148
	v_max_u32_e32 v148, v149, v143
	v_min_u32_e32 v159, v149, v143
	v_max_u32_e32 v143, v155, v142
	v_min_u32_e32 v149, v155, v142
	v_max_u32_e32 v142, v145, v158
	v_min_u32_e32 v155, v145, v158
	v_max_u32_e32 v158, v157, v156
	v_min_u32_e32 v145, v157, v156
	v_max_u32_e32 v156, v148, v154
	v_min_u32_e32 v157, v148, v154
	v_max_u32_e32 v154, v143, v147
	v_min_u32_e32 v148, v143, v147
	v_max_u32_e32 v147, v142, v159
	v_min_u32_e32 v143, v142, v159
	v_max_u32_e32 v159, v158, v149
	v_min_u32_e32 v142, v158, v149
	v_max_u32_e32 v149, v151, v155
	v_min_u32_e32 v158, v151, v155
	v_max_u32_e32 v155, v153, v145
	v_min_u32_e32 v151, v153, v145
	v_max_u32_e32 v145, v156, v152
	v_min_u32_e32 v153, v156, v152
	v_max_u32_e32 v152, v154, v157
	v_min_u32_e32 v156, v154, v157
	v_max_u32_e32 v157, v147, v148
	v_min_u32_e32 v154, v147, v148
	v_max_u32_e32 v148, v159, v143
	v_min_u32_e32 v147, v159, v143
	v_max_u32_e32 v143, v149, v142
	v_min_u32_e32 v159, v149, v142
	v_max_u32_e32 v142, v155, v158
	v_min_u32_e32 v149, v155, v158
	v_max_u32_e32 v158, v146, v151
	v_min_u32_e32 v155, v146, v151
	v_max_u32_e32 v151, v29, v24
	v_min_u32_e32 v146, v29, v24
	v_max_u32_e32 v160, v27, v23
	v_min_u32_e32 v161, v27, v23
	v_max_u32_e32 v162, v26, v22
	v_min_u32_e32 v163, v26, v22
	v_max_u32_e32 v164, v25, v20
	v_min_u32_e32 v165, v25, v20
	v_max_u32_e32 v166, v151, v162
	v_min_u32_e32 v167, v151, v162
	v_max_u32_e32 v162, v160, v164
	v_min_u32_e32 v151, v160, v164
	v_max_u32_e32 v164, v146, v163
	v_min_u32_e32 v160, v146, v163
	v_max_u32_e32 v163, v161, v165
	v_min_u32_e32 v146, v161, v165
	v_max_u32_e32 v165, v167, v164
	v_min_u32_e32 v161, v167, v164
	v_max_u32_e32 v164, v151, v163
	v_min_u32_e32 v167, v151, v163
	v_max_u32_e32 v163, v166, v162
	v_min_u32_e32 v151, v166, v162
	v_max_u32_e32 v162, v165, v164
	v_min_u32_e32 v166, v165, v164
	v_max_u32_e32 v164, v161, v167
	v_min_u32_e32 v165, v161, v167
	v_max_u32_e32 v167, v160, v146
	v_min_u32_e32 v161, v160, v146
	v_max_u32_e32 v146, v151, v164
	v_min_u32_e32 v160, v151, v164
	v_max_u32_e32 v164, v166, v167
	v_min_u32_e32 v151, v166, v167
	v_max_u32_e32 v167, v146, v162
	v_min_u32_e32 v166, v146, v162
	v_max_u32_e32 v162, v164, v160
	v_min_u32_e32 v146, v164, v160
	v_max_u32_e32 v160, v165, v151
	v_min_u32_e32 v164, v165, v151
	s_mov_b32 s12, 0
	s_mov_b32 s13, 31
.LBB0_1062:
	s_lshl_b32 s14, 1, s13
	s_or_b32 s14, s14, s12
	v_cmp_ge_u32_e64 s[4:5], v148, s14
	v_cmp_ge_u32_e64 s[18:19], v162, s14
	v_cmp_ge_u32_e64 s[16:17], v144, s14
	v_cmp_ge_u32_e64 s[24:25], v161, s14
	v_cndmask_b32_e64 v134, v152, v142, s[4:5]
	v_cndmask_b32_e64 v138, v167, v160, s[18:19]
	v_cmp_ge_u32_e64 s[6:7], v134, s14
	v_cmp_ge_u32_e64 s[20:21], v138, s14
	s_nop 0
	v_cndmask_b32_e64 v134, v145, v157, s[6:7]
	v_cndmask_b32_e64 v138, v163, v166, s[20:21]
	v_cndmask_b32_e64 v135, v143, v158, s[6:7]
	v_cndmask_b32_e64 v139, v146, v164, s[20:21]
	v_cndmask_b32_e64 v134, v134, v135, s[4:5]
	v_cndmask_b32_e64 v138, v138, v139, s[18:19]
	v_cmp_ge_u32_e64 s[8:9], v134, s14
	v_cmp_ge_u32_e64 s[22:23], v138, s14
	s_nop 0
	v_cndmask_b32_e64 v134, v150, v153, s[8:9]
	v_cndmask_b32_e64 v135, v156, v154, s[8:9]
	v_cndmask_b32_e64 v136, v147, v159, s[8:9]
	v_cndmask_b32_e64 v137, v149, v155, s[8:9]
	v_cndmask_b32_e64 v134, v134, v135, s[6:7]
	v_cndmask_b32_e64 v136, v136, v137, s[6:7]
	v_cndmask_b32_e64 v134, v134, v136, s[4:5]
	v_cmp_ge_u32_e64 s[10:11], v134, s14
	s_bcnt1_i32_b64 s1, s[4:5]
	s_mov_b32 s0, s1
	s_bcnt1_i32_b64 s1, s[6:7]
	s_lshl1_add_u32 s0, s0, s1
	s_bcnt1_i32_b64 s1, s[8:9]
	s_lshl1_add_u32 s0, s0, s1
	s_bcnt1_i32_b64 s1, s[10:11]
	s_lshl1_add_u32 s0, s0, s1
	s_bcnt1_i32_b64 s1, s[16:17]
	s_add_i32 s0, s0, s1
	s_mov_b32 s2, s0
	s_bcnt1_i32_b64 s1, s[18:19]
	s_mov_b32 s0, s1
	s_bcnt1_i32_b64 s1, s[20:21]
	s_lshl1_add_u32 s0, s0, s1
	s_bcnt1_i32_b64 s1, s[22:23]
	s_lshl1_add_u32 s0, s0, s1
	s_bcnt1_i32_b64 s1, s[24:25]
	s_add_i32 s0, s0, s1
	s_add_i32 s2, s2, s0
	s_cmpk_ge_u32 s2, 0x100
	s_cselect_b32 s12, s14, s12
	s_cmpk_eq_u32 s2, 0x100
	s_cbranch_scc1 .Lbt_exit_24
	s_sub_u32 s13, s13, 1
	s_cbranch_scc0 .LBB0_1062
.Lbt_exit_24:
	v_mov_b32_e32 v21, s12
	s_cmpk_eq_i32 s2, 0x100
	s_cbranch_scc1 .Lselfast_24
	v_cmp_gt_u32_e32 vcc, v18, v21
	s_bcnt1_i32_b64 s50, vcc
	v_cmp_gt_u32_e32 vcc, v19, v21
	s_bcnt1_i32_b64 s51, vcc
	v_cmp_gt_u32_e32 vcc, v14, v21
	v_cmp_gt_u32_e64 s[48:49], v20, v21
	s_bcnt1_i32_b64 s52, vcc
	v_cmp_gt_u32_e32 vcc, v15, v21
	s_bcnt1_i32_b64 s48, s[48:49]
	s_add_i32 s49, s50, s51
	s_bcnt1_i32_b64 s53, vcc
	v_cmp_gt_u32_e32 vcc, v12, v21
	s_add_i32 s49, s49, s52
	s_bcnt1_i32_b64 s54, vcc
	v_cmp_gt_u32_e32 vcc, v13, v21
	s_add_i32 s49, s49, s53
	s_bcnt1_i32_b64 s55, vcc
	v_cmp_gt_u32_e32 vcc, v10, v21
	s_add_i32 s49, s49, s54
	s_bcnt1_i32_b64 s56, vcc
	v_cmp_gt_u32_e32 vcc, v11, v21
	s_add_i32 s49, s49, s55
	s_bcnt1_i32_b64 s57, vcc
	v_cmp_gt_u32_e32 vcc, v8, v21
	s_add_i32 s49, s49, s56
	s_bcnt1_i32_b64 s58, vcc
	v_cmp_gt_u32_e32 vcc, v9, v21
	s_add_i32 s49, s49, s57
	s_bcnt1_i32_b64 s59, vcc
	v_cmp_gt_u32_e32 vcc, v6, v21
	s_add_i32 s49, s49, s58
	s_bcnt1_i32_b64 s60, vcc
	v_cmp_gt_u32_e32 vcc, v7, v21
	s_add_i32 s49, s49, s59
	s_bcnt1_i32_b64 s61, vcc
	v_cmp_gt_u32_e32 vcc, v4, v21
	s_add_i32 s49, s49, s60
	s_bcnt1_i32_b64 s62, vcc
	v_cmp_gt_u32_e32 vcc, v5, v21
	s_add_i32 s49, s49, s61
	s_bcnt1_i32_b64 s63, vcc
	v_cmp_gt_u32_e32 vcc, v2, v21
	s_add_i32 s49, s49, s62
	s_bcnt1_i32_b64 s64, vcc
	v_cmp_gt_u32_e32 vcc, v3, v21
	s_add_i32 s49, s49, s63
	s_bcnt1_i32_b64 s65, vcc
	v_cmp_gt_u32_e32 vcc, v29, v21
	s_add_i32 s49, s49, s64
	s_bcnt1_i32_b64 s66, vcc
	v_cmp_gt_u32_e32 vcc, v27, v21
	s_add_i32 s49, s49, s65
	s_bcnt1_i32_b64 s67, vcc
	v_cmp_gt_u32_e32 vcc, v26, v21
	s_add_i32 s49, s49, s66
	s_bcnt1_i32_b64 s68, vcc
	v_cmp_gt_u32_e32 vcc, v25, v21
	s_add_i32 s49, s49, s67
	s_bcnt1_i32_b64 s69, vcc
	v_cmp_gt_u32_e32 vcc, v24, v21
	s_add_i32 s49, s49, s68
	s_bcnt1_i32_b64 s73, vcc
	v_cmp_gt_u32_e32 vcc, v23, v21
	s_add_i32 s49, s49, s69
	s_bcnt1_i32_b64 s74, vcc
	v_cmp_gt_u32_e32 vcc, v22, v21
	s_add_i32 s49, s49, s73
	s_bcnt1_i32_b64 s75, vcc
	s_add_i32 s49, s49, s74
	s_add_i32 s49, s49, s75
	s_add_i32 s49, s49, s48
	v_cmp_le_u32_e64 s[46:47], v18, v21
	v_cmp_le_u32_e64 s[44:45], v19, v21
	v_cmp_le_u32_e64 s[42:43], v14, v21
	v_cmp_le_u32_e64 s[40:41], v15, v21
	v_cmp_le_u32_e64 s[38:39], v12, v21
	v_cmp_le_u32_e64 s[36:37], v13, v21
	v_cmp_le_u32_e64 s[34:35], v10, v21
	v_cmp_le_u32_e64 s[30:31], v11, v21
	v_cmp_le_u32_e64 s[28:29], v8, v21
	v_cmp_le_u32_e64 s[26:27], v9, v21
	v_cmp_le_u32_e64 s[24:25], v6, v21
	v_cmp_le_u32_e64 s[22:23], v7, v21
	v_cmp_le_u32_e64 s[20:21], v4, v21
	v_cmp_le_u32_e64 s[18:19], v5, v21
	v_cmp_le_u32_e64 s[16:17], v2, v21
	v_cmp_le_u32_e64 s[14:15], v3, v21
	v_cmp_le_u32_e64 s[12:13], v29, v21
	v_cmp_le_u32_e64 s[10:11], v27, v21
	v_cmp_le_u32_e64 s[8:9], v26, v21
	v_cmp_le_u32_e64 s[6:7], v25, v21
	v_cmp_le_u32_e64 s[4:5], v24, v21
	v_cmp_le_u32_e64 s[2:3], v23, v21
	v_cmp_le_u32_e64 s[0:1], v22, v21
	v_cmp_le_u32_e32 vcc, v20, v21
	s_sub_i32 s54, 0x100, s49
	v_cmp_eq_u32_e64 s[48:49], v18, v21
	s_mov_b64 s[52:53], -1
	s_and_saveexec_b64 s[50:51], s[46:47]
	v_mbcnt_lo_u32_b32 v18, s48, 0
	v_mbcnt_hi_u32_b32 v18, s49, v18
	v_cmp_gt_i32_e64 s[46:47], s54, v18
	s_and_b64 s[46:47], s[48:49], s[46:47]
	s_orn2_b64 s[52:53], s[46:47], exec
	s_or_b64 exec, exec, s[50:51]
	v_cndmask_b32_e64 v18, 0, 1, s[52:53]
	v_cmp_eq_u32_e64 s[66:67], 0, v16
	v_cmp_ne_u32_e64 s[50:51], 0, v18
	s_and_saveexec_b64 s[46:47], s[66:67]
	s_cbranch_execz .LBB0_1067
	v_mov_b64_e32 v[30:31], s[50:51]
	global_store_dwordx2 v[0:1], v[30:31], off

.LBB0_1159:
	ds_read2st64_b32 v[8:9], v28 offset1:1
	ds_read2st64_b32 v[6:7], v28 offset0:2 offset1:3
	ds_read2st64_b32 v[4:5], v28 offset0:4 offset1:5
	ds_read2st64_b32 v[2:3], v28 offset0:6 offset1:7
	v_or_b32_e32 v10, 0x200, v16
	v_cmp_gt_u32_e32 vcc, s72, v10
	v_mov_b32_e32 v19, 0
	v_mov_b32_e32 v20, 0
	s_and_saveexec_b64 s[0:1], vcc
	ds_read_b32 v20, v28 offset:2048
	s_or_b64 exec, exec, s[0:1]
	v_or_b32_e32 v10, 0x240, v16
	v_cmp_gt_u32_e32 vcc, s72, v10
	s_and_saveexec_b64 s[0:1], vcc
	ds_read_b32 v19, v28 offset:2304
	s_or_b64 exec, exec, s[0:1]
	v_or_b32_e32 v10, 0x280, v16
	v_cmp_gt_u32_e32 vcc, s72, v10
	v_mov_b32_e32 v15, 0
	v_mov_b32_e32 v18, 0
	s_and_saveexec_b64 s[0:1], vcc
	ds_read_b32 v18, v28 offset:2560
	s_or_b64 exec, exec, s[0:1]
	v_or_b32_e32 v10, 0x2c0, v16
	v_cmp_gt_u32_e32 vcc, s72, v10
	s_and_saveexec_b64 s[0:1], vcc
	ds_read_b32 v15, v28 offset:2816
	s_or_b64 exec, exec, s[0:1]
	v_or_b32_e32 v10, 0x300, v16
	v_cmp_gt_u32_e32 vcc, s72, v10
	v_mov_b32_e32 v13, 0
	v_mov_b32_e32 v14, 0
	s_and_saveexec_b64 s[0:1], vcc
	ds_read_b32 v14, v28 offset:3072
	s_or_b64 exec, exec, s[0:1]
	v_or_b32_e32 v10, 0x340, v16
	v_cmp_gt_u32_e32 vcc, s72, v10
	s_and_saveexec_b64 s[0:1], vcc
	ds_read_b32 v13, v28 offset:3328
	s_or_b64 exec, exec, s[0:1]
	v_or_b32_e32 v10, 0x380, v16
	v_cmp_gt_u32_e32 vcc, s72, v10
	v_mov_b32_e32 v10, 0
	v_mov_b32_e32 v12, 0
	s_and_saveexec_b64 s[0:1], vcc
	ds_read_b32 v12, v28 offset:3584
	s_or_b64 exec, exec, s[0:1]
	v_or_b32_e32 v11, 0x3c0, v16
	v_cmp_gt_u32_e32 vcc, s72, v11
	s_and_saveexec_b64 s[0:1], vcc
	ds_read_b32 v10, v28 offset:3840
	s_or_b64 exec, exec, s[0:1]
	v_mov_b32_e32 v21, 31
	v_mov_b32_e32 v11, 0
	s_waitcnt lgkmcnt(0)
	s_waitcnt vmcnt(0)
	v_max_u32_e32 v142, v8, v20
	v_min_u32_e32 v143, v8, v20
	v_max_u32_e32 v144, v9, v19
	v_min_u32_e32 v145, v9, v19
	v_max_u32_e32 v146, v6, v18
	v_min_u32_e32 v147, v6, v18
	v_max_u32_e32 v148, v7, v15
	v_min_u32_e32 v149, v7, v15
	v_max_u32_e32 v150, v4, v14
	v_min_u32_e32 v151, v4, v14
	v_max_u32_e32 v152, v5, v13
	v_min_u32_e32 v153, v5, v13
	v_max_u32_e32 v154, v2, v12
	v_min_u32_e32 v155, v2, v12
	v_max_u32_e32 v156, v3, v10
	v_min_u32_e32 v157, v3, v10
	v_max_u32_e32 v158, v142, v150
	v_min_u32_e32 v159, v142, v150
	v_max_u32_e32 v150, v144, v152
	v_min_u32_e32 v142, v144, v152
	v_max_u32_e32 v152, v146, v154
	v_min_u32_e32 v144, v146, v154
	v_max_u32_e32 v154, v148, v156
	v_min_u32_e32 v146, v148, v156
	v_max_u32_e32 v156, v143, v151
	v_min_u32_e32 v148, v143, v151
	v_max_u32_e32 v151, v145, v153
	v_min_u32_e32 v143, v145, v153
	v_max_u32_e32 v153, v147, v155
	v_min_u32_e32 v145, v147, v155
	v_max_u32_e32 v155, v149, v157
	v_min_u32_e32 v147, v149, v157
	v_max_u32_e32 v157, v159, v156
	v_min_u32_e32 v149, v159, v156
	v_max_u32_e32 v156, v142, v151
	v_min_u32_e32 v159, v142, v151
	v_max_u32_e32 v151, v144, v153
	v_min_u32_e32 v142, v144, v153
	v_max_u32_e32 v153, v146, v155
	v_min_u32_e32 v144, v146, v155
	v_max_u32_e32 v155, v158, v152
	v_min_u32_e32 v146, v158, v152
	v_max_u32_e32 v152, v150, v154
	v_min_u32_e32 v158, v150, v154
	v_max_u32_e32 v154, v157, v151
	v_min_u32_e32 v150, v157, v151
	v_max_u32_e32 v151, v156, v153
	v_min_u32_e32 v157, v156, v153
	v_max_u32_e32 v153, v149, v142
	v_min_u32_e32 v156, v149, v142
	v_max_u32_e32 v142, v159, v144
	v_min_u32_e32 v149, v159, v144
	v_max_u32_e32 v144, v148, v145
	v_min_u32_e32 v159, v148, v145
	v_max_u32_e32 v145, v143, v147
	v_min_u32_e32 v148, v143, v147
	v_max_u32_e32 v147, v146, v153
	v_min_u32_e32 v143, v146, v153
	v_max_u32_e32 v153, v158, v142
	v_min_u32_e32 v146, v158, v142
	v_max_u32_e32 v142, v150, v144
	v_min_u32_e32 v158, v150, v144
	v_max_u32_e32 v144, v157, v145
	v_min_u32_e32 v150, v157, v145
	v_max_u32_e32 v145, v147, v154
	v_min_u32_e32 v157, v147, v154
	v_max_u32_e32 v154, v153, v151
	v_min_u32_e32 v147, v153, v151
	v_max_u32_e32 v151, v142, v143
	v_min_u32_e32 v153, v142, v143
	v_max_u32_e32 v143, v144, v146
	v_min_u32_e32 v142, v144, v146
	v_max_u32_e32 v146, v156, v158
	v_min_u32_e32 v144, v156, v158
	v_max_u32_e32 v158, v149, v150
	v_min_u32_e32 v156, v149, v150
	v_max_u32_e32 v150, v155, v152
	v_min_u32_e32 v149, v155, v152
	v_max_u32_e32 v152, v145, v154
	v_min_u32_e32 v155, v145, v154
	v_max_u32_e32 v154, v157, v147
	v_min_u32_e32 v145, v157, v147
	v_max_u32_e32 v147, v151, v143
	v_min_u32_e32 v157, v151, v143
	v_max_u32_e32 v143, v153, v142
	v_min_u32_e32 v151, v153, v142
	v_max_u32_e32 v142, v146, v158
	v_min_u32_e32 v153, v146, v158
	v_max_u32_e32 v158, v144, v156
	v_min_u32_e32 v146, v144, v156
	v_max_u32_e32 v156, v159, v148
	v_min_u32_e32 v144, v159, v148
	v_max_u32_e32 v148, v149, v143
	v_min_u32_e32 v159, v149, v143
	v_max_u32_e32 v143, v155, v142
	v_min_u32_e32 v149, v155, v142
	v_max_u32_e32 v142, v145, v158
	v_min_u32_e32 v155, v145, v158
	v_max_u32_e32 v158, v157, v156
	v_min_u32_e32 v145, v157, v156
	v_max_u32_e32 v156, v148, v154
	v_min_u32_e32 v157, v148, v154
	v_max_u32_e32 v154, v143, v147
	v_min_u32_e32 v148, v143, v147
	v_max_u32_e32 v147, v142, v159
	v_min_u32_e32 v143, v142, v159
	v_max_u32_e32 v159, v158, v149
	v_min_u32_e32 v142, v158, v149
	v_max_u32_e32 v149, v151, v155
	v_min_u32_e32 v158, v151, v155
	v_max_u32_e32 v155, v153, v145
	v_min_u32_e32 v151, v153, v145
	v_max_u32_e32 v145, v156, v152
	v_min_u32_e32 v153, v156, v152
	v_max_u32_e32 v152, v154, v157
	v_min_u32_e32 v156, v154, v157
	v_max_u32_e32 v157, v147, v148
	v_min_u32_e32 v154, v147, v148
	v_max_u32_e32 v148, v159, v143
	v_min_u32_e32 v147, v159, v143
	v_max_u32_e32 v143, v149, v142
	v_min_u32_e32 v159, v149, v142
	v_max_u32_e32 v142, v155, v158
	v_min_u32_e32 v149, v155, v158
	v_max_u32_e32 v158, v146, v151
	v_min_u32_e32 v155, v146, v151
	s_mov_b32 s12, 0
	s_mov_b32 s13, 31
.LBB0_1176:
	s_lshl_b32 s14, 1, s13
	s_or_b32 s14, s14, s12
	v_cmp_ge_u32_e64 s[4:5], v148, s14
	v_cmp_ge_u32_e64 s[16:17], v144, s14
	s_nop 0
	v_cndmask_b32_e64 v134, v152, v142, s[4:5]
	v_cmp_ge_u32_e64 s[6:7], v134, s14
	s_nop 1
	v_cndmask_b32_e64 v134, v145, v157, s[6:7]
	v_cndmask_b32_e64 v135, v143, v158, s[6:7]
	v_cndmask_b32_e64 v134, v134, v135, s[4:5]
	v_cmp_ge_u32_e64 s[8:9], v134, s14
	s_nop 1
	v_cndmask_b32_e64 v134, v150, v153, s[8:9]
	v_cndmask_b32_e64 v135, v156, v154, s[8:9]
	v_cndmask_b32_e64 v136, v147, v159, s[8:9]
	v_cndmask_b32_e64 v137, v149, v155, s[8:9]
	v_cndmask_b32_e64 v134, v134, v135, s[6:7]
	v_cndmask_b32_e64 v136, v136, v137, s[6:7]
	v_cndmask_b32_e64 v134, v134, v136, s[4:5]
	v_cmp_ge_u32_e64 s[10:11], v134, s14
	s_bcnt1_i32_b64 s1, s[4:5]
	s_mov_b32 s0, s1
	s_bcnt1_i32_b64 s1, s[6:7]
	s_lshl1_add_u32 s0, s0, s1
	s_bcnt1_i32_b64 s1, s[8:9]
	s_lshl1_add_u32 s0, s0, s1
	s_bcnt1_i32_b64 s1, s[10:11]
	s_lshl1_add_u32 s0, s0, s1
	s_bcnt1_i32_b64 s1, s[16:17]
	s_add_i32 s0, s0, s1
	s_mov_b32 s2, s0
	s_cmpk_ge_u32 s2, 0x100
	s_cselect_b32 s12, s14, s12
	s_cmpk_eq_u32 s2, 0x100
	s_cbranch_scc1 .Lbt_exit_16
	s_sub_u32 s13, s13, 1
	s_cbranch_scc0 .LBB0_1176
.Lbt_exit_16:
	v_mov_b32_e32 v11, s12
	s_cmpk_eq_i32 s2, 0x100
	s_cbranch_scc1 .Lselfast_16
	v_cmp_gt_u32_e32 vcc, v8, v11
	s_bcnt1_i32_b64 s34, vcc
	v_cmp_gt_u32_e32 vcc, v9, v11
	s_bcnt1_i32_b64 s35, vcc
	v_cmp_gt_u32_e32 vcc, v6, v11
	v_cmp_gt_u32_e64 s[28:29], v10, v11
	s_bcnt1_i32_b64 s36, vcc
	v_cmp_gt_u32_e32 vcc, v7, v11
	s_bcnt1_i32_b64 s28, s[28:29]
	s_add_i32 s29, s34, s35
	s_bcnt1_i32_b64 s37, vcc
	v_cmp_gt_u32_e32 vcc, v4, v11
	s_add_i32 s29, s29, s36
	s_bcnt1_i32_b64 s38, vcc
	v_cmp_gt_u32_e32 vcc, v5, v11
	s_add_i32 s29, s29, s37
	s_bcnt1_i32_b64 s39, vcc
	v_cmp_gt_u32_e32 vcc, v2, v11
	s_add_i32 s29, s29, s38
	s_bcnt1_i32_b64 s40, vcc
	v_cmp_gt_u32_e32 vcc, v3, v11
	s_add_i32 s29, s29, s39
	s_bcnt1_i32_b64 s41, vcc
	v_cmp_gt_u32_e32 vcc, v20, v11
	s_add_i32 s29, s29, s40
	s_bcnt1_i32_b64 s42, vcc
	v_cmp_gt_u32_e32 vcc, v19, v11
	s_add_i32 s29, s29, s41
	s_bcnt1_i32_b64 s43, vcc
	v_cmp_gt_u32_e32 vcc, v18, v11
	s_add_i32 s29, s29, s42
	s_bcnt1_i32_b64 s44, vcc
	v_cmp_gt_u32_e32 vcc, v15, v11
	s_add_i32 s29, s29, s43
	s_bcnt1_i32_b64 s45, vcc
	v_cmp_gt_u32_e32 vcc, v14, v11
	s_add_i32 s29, s29, s44
	s_bcnt1_i32_b64 s46, vcc
	v_cmp_gt_u32_e32 vcc, v13, v11
	s_add_i32 s29, s29, s45
	s_bcnt1_i32_b64 s47, vcc
	v_cmp_gt_u32_e32 vcc, v12, v11
	s_add_i32 s29, s29, s46
	s_bcnt1_i32_b64 s48, vcc
	s_add_i32 s29, s29, s47
	s_add_i32 s29, s29, s48
	s_add_i32 s29, s29, s28
	v_cmp_le_u32_e64 s[30:31], v8, v11
	v_cmp_le_u32_e64 s[26:27], v9, v11
	v_cmp_le_u32_e64 s[24:25], v6, v11
	v_cmp_le_u32_e64 s[22:23], v7, v11
	v_cmp_le_u32_e64 s[20:21], v4, v11
	v_cmp_le_u32_e64 s[18:19], v5, v11
	v_cmp_le_u32_e64 s[16:17], v2, v11
	v_cmp_le_u32_e64 s[14:15], v3, v11
	v_cmp_le_u32_e64 s[12:13], v20, v11
	v_cmp_le_u32_e64 s[10:11], v19, v11
	v_cmp_le_u32_e64 s[8:9], v18, v11
	v_cmp_le_u32_e64 s[6:7], v15, v11
	v_cmp_le_u32_e64 s[4:5], v14, v11
	v_cmp_le_u32_e64 s[2:3], v13, v11
	v_cmp_le_u32_e64 s[0:1], v12, v11
	v_cmp_le_u32_e32 vcc, v10, v11
	s_sub_i32 s38, 0x100, s29
	v_cmp_eq_u32_e64 s[28:29], v8, v11
	s_mov_b64 s[36:37], -1
	s_and_saveexec_b64 s[34:35], s[30:31]
	v_mbcnt_lo_u32_b32 v8, s28, 0
	v_mbcnt_hi_u32_b32 v8, s29, v8
	v_cmp_gt_i32_e64 s[30:31], s38, v8
	s_and_b64 s[30:31], s[28:29], s[30:31]
	s_orn2_b64 s[36:37], s[30:31], exec
	s_or_b64 exec, exec, s[34:35]
	v_cndmask_b32_e64 v8, 0, 1, s[36:37]
	v_cmp_eq_u32_e64 s[66:67], 0, v16
	v_cmp_ne_u32_e64 s[34:35], 0, v8
	s_and_saveexec_b64 s[30:31], s[66:67]
	s_cbranch_execz .LBB0_1181
	v_mov_b64_e32 v[22:23], s[34:35]
	global_store_dwordx2 v[0:1], v[22:23], off
